# P8 K image XOR swizzle widened from 8 to 16 slots (row&15) to remove the 2-way ds_read_b128 bank conflict on K fragment reads
# speedup vs baseline: 1.0064x; 1.0017x over previous
.LBB0_960:
	s_cmpk_gt_i32 s49, 0x3ff
	s_cbranch_scc1 .LBB0_1070
	s_add_u32 s31, s38, 0x4000000
	s_addc_u32 s51, s39, 0
	s_add_u32 s52, s38, 0x10000000
	s_addc_u32 s53, s39, 0
	s_add_u32 s72, s36, 0x4000000
	v_lshlrev_b32_e32 v4, 4, v0
	v_lshrrev_b32_e32 v177, 5, v198
	s_addc_u32 s73, s37, 0
	s_movk_i32 s12, 0xc0
	v_lshlrev_b32_e32 v164, 4, v177
	v_and_b32_e32 v8, 0xf0, v4
	s_add_u32 s74, s38, 0x2400000
	v_and_b32_e32 v5, 0xc0, v4
	v_and_b32_e32 v6, 32, v3
	v_and_b32_e32 v2, 0x118, v2
	v_bitop3_b32 v186, v164, v8, s12 bitop3:0x36
	s_movk_i32 s12, 0xe0
	s_addc_u32 s75, s39, 0
	v_or3_b32 v3, v6, v5, v2
	v_bitop3_b32 v187, v164, v8, s12 bitop3:0x36
	s_add_i32 s12, 0, 0x14000
	v_add_u32_e32 v189, s12, v3
	s_add_i32 s12, 0, 0x18000
	s_add_i32 s76, 0, 0x10000
	s_add_i32 s14, 0, 0x22400
	v_add_u32_e32 v190, s12, v3
	s_add_i32 s12, 0, 0x1c000
	s_add_u32 s78, s38, 0x8000000
	s_addc_u32 s79, s39, 0
	s_add_u32 s80, s38, 0xc000000
	v_and_b32_e32 v176, 31, v0
	s_movk_i32 s77, 0xf0
	s_addc_u32 s81, s39, 0
	v_lshlrev_b32_e32 v7, 8, v176
	v_bitop3_b32 v180, v164, v4, s77 bitop3:0x78
	v_or_b32_e32 v4, 32, v164
	s_add_u32 s56, s38, 0x2200000
	v_or_b32_e32 v9, 64, v164
	v_add_u32_e32 v191, s12, v3
	s_addc_u32 s57, s39, 0
	s_add_i32 s12, 0, 0x22100
	v_bitop3_b32 v4, v4, v7, v8 bitop3:0xde
	v_or_b32_e32 v10, 0x60, v164
	s_add_u32 s58, s38, 0x2000000
	v_add_u32_e32 v212, 0, v4
	v_bitop3_b32 v4, v9, v7, v8 bitop3:0xde
	v_or_b32_e32 v11, 0x80, v164
	s_addc_u32 s59, s39, 0
	v_add_u32_e32 v213, 0, v4
	v_bitop3_b32 v4, v10, v7, v8 bitop3:0xde
	v_or_b32_e32 v12, 0xa0, v164
	v_mov_b32_e32 v15, 0x7c
	s_cmp_eq_u32 s45, 7
	v_add_u32_e32 v214, 0, v4
	v_bitop3_b32 v4, v11, v7, v8 bitop3:0xde
	v_lshl_add_u32 v179, v176, 2, s14
	s_movk_i32 s14, 0x60
	v_or_b32_e32 v13, 0xc0, v164
	v_lshl_or_b32 v192, v1, 2, v15
	v_lshlrev_b32_e32 v15, 2, v198
	s_cselect_b64 s[60:61], -1, 0
	s_cmp_lg_u32 s45, 7
	v_add_u32_e32 v215, 0, v4
	v_bitop3_b32 v4, v12, v7, v8 bitop3:0xde
	v_bitop3_b32 v183, v164, v8, s14 bitop3:0x36
	s_movk_i32 s14, 0x80
	v_or_b32_e32 v14, 0xe0, v164
	v_add_u32_e32 v193, s12, v15
	s_cselect_b64 s[62:63], -1, 0
	s_add_i32 s12, 0, 0x27000
	v_add_u32_e32 v216, 0, v4
	v_bitop3_b32 v4, v13, v7, v8 bitop3:0xde
	s_mov_b32 s13, 0x10000
	v_add_u32_e32 v178, s76, v3
	v_bitop3_b32 v184, v164, v8, s14 bitop3:0x36
	s_movk_i32 s14, 0xa0
	v_mov_b32_e32 v3, 0
	v_or_b32_e32 v194, 64, v198
	v_or_b32_e32 v195, 0x80, v198
	v_or_b32_e32 v196, 0xc0, v198
	v_or_b32_e32 v197, 0x100, v198
	v_or_b32_e32 v199, 0x140, v198
	v_or_b32_e32 v200, 0x180, v198
	v_or_b32_e32 v201, 0x1c0, v198
	v_add_u32_e32 v202, s12, v15
	v_bitop3_b32 v15, v164, v7, v8 bitop3:0xde
	v_add_u32_e32 v217, 0, v4
	v_bitop3_b32 v4, v14, v7, v8 bitop3:0xde
	v_add3_u32 v2, v2, 0, v5
	s_mov_b32 s55, 0
	v_bitop3_b32 v181, v164, v8, 32 bitop3:0x36
	v_bitop3_b32 v182, v164, v8, 64 bitop3:0x36
	v_bitop3_b32 v185, v164, v8, s14 bitop3:0x36
	v_lshlrev_b32_e32 v188, 2, v177
	v_mov_b32_e32 v165, v3
	s_movk_i32 s45, 0x100
	v_lshl_add_u32 v203, v194, 2, s12
	v_lshl_add_u32 v204, v195, 2, s12
	v_lshl_add_u32 v205, v196, 2, s12
	v_lshl_add_u32 v206, v197, 2, s12
	v_lshl_add_u32 v207, v199, 2, s12
	v_lshl_add_u32 v208, v200, 2, s12
	v_lshl_add_u32 v209, v201, 2, s12
	v_add_u32_e32 v210, 0, v7
	v_add_u32_e32 v211, 0, v15
	v_add_u32_e32 v218, 0, v4
	v_add3_u32 v219, v2, v6, s13
	s_movk_i32 s82, 0x600
	s_add_i32 s83, 0, 0x22200
	s_movk_i32 s84, 0x90
	s_mov_b32 s85, 0x6050400
	s_mov_b32 s86, 0xff0000
	s_add_i32 s87, 0, 0x22040
	s_mov_b32 s88, 0xefa18f08
	s_mov_b32 s89, 0x41000000
	v_mov_b32_e32 v220, 0xf149f2ca
	s_mov_b32 s90, 0
	s_branch .LBB0_965
